# v45: v41 + redundant workgroup barrier removed at 20 phase seams (kept only on the skip path)
# baseline (speedup 1.0000x reference)
.LBB0_276:
	s_cmp_lt_i32 s59, 2
	s_cbranch_scc1 .Lsb0
	s_waitcnt vmcnt(0)
	s_barrier
	s_and_saveexec_b64 s[2:3], s[0:1]
	s_cbranch_execz .LBB0_329
	s_waitcnt vmcnt(0) lgkmcnt(0)
	v_mov_b32_e32 v241, 0
	v_lshlrev_b32_e64 v254, 8, s31
	v_mov_b32_e32 v247, 1
	v_add_u32_e32 v246, 0x1400, v254
	global_atomic_add v248, v246, v247, s[60:61] sc0
	buffer_inv sc1

.Lsb0:
	s_barrier
	s_branch .LBB0_330

.LBB0_338:
	s_cmp_lt_i32 s59, 3
	s_cbranch_scc1 .Lsb1
	s_waitcnt vmcnt(0)
	s_barrier
	s_and_saveexec_b64 s[2:3], s[0:1]
	s_cbranch_execz .LBB0_391
	s_waitcnt vmcnt(0) lgkmcnt(0)
	v_mov_b32_e32 v241, 0
	v_lshlrev_b32_e64 v254, 8, s31
	v_mov_b32_e32 v247, 1
	v_add_u32_e32 v246, 0x1400, v254
	global_atomic_add v248, v246, v247, s[60:61] sc0
	buffer_inv sc1

.LBB0_587:
	s_cmp_lt_i32 s59, 4
	s_waitcnt vmcnt(0)
	s_cbranch_scc1 .Lsb2
	s_waitcnt vmcnt(0)
	s_setprio 0
	s_barrier
	s_and_saveexec_b64 s[2:3], s[0:1]
	s_cbranch_execz .LBB0_640
	s_waitcnt vmcnt(0) lgkmcnt(0)
	v_mov_b32_e32 v241, 0
	v_lshlrev_b32_e64 v254, 8, s31
	v_mov_b32_e32 v247, 1
	v_mov_b32_e32 v246, 0x3600
	global_atomic_add v248, v246, v247, s[60:61] sc0
	buffer_inv sc1

.LBB0_657:
	s_cmp_lt_i32 s59, 5
	s_cbranch_scc1 .Lsb3
	s_waitcnt vmcnt(0)
	s_barrier
	s_and_saveexec_b64 s[2:3], s[0:1]
	s_cbranch_execz .LBB0_710
	s_waitcnt vmcnt(0) lgkmcnt(0)
	v_mov_b32_e32 v241, 0
	v_lshlrev_b32_e64 v254, 8, s31
	v_mov_b32_e32 v247, 1
	v_add_u32_e32 v246, 0x1400, v254
	global_atomic_add v248, v246, v247, s[60:61] sc0
	buffer_inv sc1

.LBB0_833:
	s_cmp_lt_i32 s59, 6
	s_waitcnt vmcnt(0)
	s_cbranch_scc1 .Lsb4
	s_waitcnt vmcnt(0)
	s_barrier
	s_and_saveexec_b64 s[2:3], s[0:1]
	s_cbranch_execz .LBB0_886
	s_waitcnt vmcnt(0) lgkmcnt(0)
	v_mov_b32_e32 v241, 0
	v_lshlrev_b32_e64 v254, 8, s31
	v_mov_b32_e32 v247, 1
	v_mov_b32_e32 v246, 0x3600
	global_atomic_add v248, v246, v247, s[60:61] sc0
	buffer_inv sc1

.LBB0_986:
	s_cmp_lt_i32 s59, 7
	s_cbranch_scc1 .Lsb5
	s_waitcnt vmcnt(0)
	s_barrier
	s_and_saveexec_b64 s[2:3], s[0:1]
	s_cbranch_execz .LBB0_1039
	s_waitcnt vmcnt(0) lgkmcnt(0)
	v_mov_b32_e32 v241, 0
	v_lshlrev_b32_e64 v254, 8, s31
	v_mov_b32_e32 v247, 1
	v_add_u32_e32 v246, 0x1400, v254
	global_atomic_add v248, v246, v247, s[60:61] sc0
	buffer_inv sc1

.LBB0_1106:
	s_cmp_lt_i32 s59, 8
	s_cbranch_scc1 .Lsb6
	s_waitcnt vmcnt(0)
	s_barrier
	s_and_saveexec_b64 s[2:3], s[0:1]
	s_cbranch_execz .LBB0_1159
	s_waitcnt vmcnt(0) lgkmcnt(0)
	v_mov_b32_e32 v241, 0
	v_lshlrev_b32_e64 v254, 8, s31
	v_mov_b32_e32 v247, 1
	v_add_u32_e32 v246, 0x1400, v254
	global_atomic_add v248, v246, v247, s[60:61] sc0
	buffer_inv sc1

.LBB0_1285:
	s_cmp_lt_i32 s59, 10
	s_waitcnt vmcnt(0)
	s_cbranch_scc1 .Lsb7
	s_waitcnt vmcnt(0)
	s_setprio 0
	s_barrier
	s_and_saveexec_b64 s[2:3], s[0:1]
	s_cbranch_execz .LBB0_1338
	s_waitcnt vmcnt(0) lgkmcnt(0)
	v_mov_b32_e32 v241, 0
	v_lshlrev_b32_e64 v254, 8, s31
	v_mov_b32_e32 v247, 1
	v_mov_b32_e32 v246, 0x3600
	global_atomic_add v248, v246, v247, s[60:61] sc0
	buffer_inv sc1

.LBB0_1347:
	s_cmp_lt_i32 s59, 11
	s_cbranch_scc1 .Lsb8
	s_waitcnt vmcnt(0)
	s_barrier
	s_and_saveexec_b64 s[2:3], s[0:1]
	s_cbranch_execz .LBB0_1400
	s_waitcnt vmcnt(0) lgkmcnt(0)
	v_mov_b32_e32 v241, 0
	v_lshlrev_b32_e64 v254, 8, s31
	v_mov_b32_e32 v247, 1
	v_add_u32_e32 v246, 0x1400, v254
	global_atomic_add v248, v246, v247, s[60:61] sc0
	buffer_inv sc1

.Lcv4_2:
.LBB0_1558:
	s_cmp_lt_i32 s59, 12
	s_waitcnt lgkmcnt(0)
	s_cbranch_scc1 .Lsb9
	s_waitcnt vmcnt(0)
	s_setprio 0
	s_barrier
	s_and_saveexec_b64 s[2:3], s[0:1]
	s_cbranch_execz .LBB0_1611
	s_waitcnt vmcnt(0) lgkmcnt(0)
	v_mov_b32_e32 v241, 0
	v_lshlrev_b32_e64 v254, 8, s31
	v_mov_b32_e32 v247, 1
	v_mov_b32_e32 v246, 0x3600
	global_atomic_add v248, v246, v247, s[60:61] sc0
	buffer_inv sc1

.LBB0_2400:
	s_cmp_lt_i32 s59, 14
	s_waitcnt vmcnt(0)
	s_cbranch_scc1 .Lsb10
	s_waitcnt vmcnt(0)
	s_setprio 0
	s_barrier
	s_and_saveexec_b64 s[2:3], s[0:1]
	s_cbranch_execz .LBB0_2453
	s_waitcnt vmcnt(0) lgkmcnt(0)
	v_mov_b32_e32 v241, 0
	v_lshlrev_b32_e64 v254, 8, s31
	v_mov_b32_e32 v247, 1
	v_mov_b32_e32 v246, 0x3600
	global_atomic_add v248, v246, v247, s[60:61] sc0
	buffer_inv sc1

.LBB0_2462:
	s_cmp_lt_i32 s59, 15
	s_cbranch_scc1 .Lsb11
	s_waitcnt vmcnt(0)
	s_barrier
	s_and_saveexec_b64 s[2:3], s[0:1]
	s_cbranch_execz .LBB0_2515
	s_waitcnt vmcnt(0) lgkmcnt(0)
	v_mov_b32_e32 v241, 0
	v_lshlrev_b32_e64 v254, 8, s31
	v_mov_b32_e32 v247, 1
	v_add_u32_e32 v246, 0x1400, v254
	global_atomic_add v248, v246, v247, s[60:61] sc0
	buffer_inv sc1

.LBB0_2579:
	s_cmp_lt_i32 s59, 16
	s_waitcnt vmcnt(0)
	s_cbranch_scc1 .Lsb12
	s_waitcnt vmcnt(0)
	s_setprio 0
	s_barrier
	s_and_saveexec_b64 s[2:3], s[0:1]
	s_cbranch_execz .LBB0_2633
	s_waitcnt vmcnt(0) lgkmcnt(0)
	v_mov_b32_e32 v241, 0
	v_lshlrev_b32_e64 v254, 8, s31
	v_mov_b32_e32 v247, 1
	v_mov_b32_e32 v246, 0x3600
	global_atomic_add v248, v246, v247, s[60:61] sc0
	buffer_inv sc1

.LBB0_2702:
	s_cmp_lt_i32 s59, 17
	s_cbranch_scc1 .Lsb13
	s_waitcnt vmcnt(0)
	s_barrier
	s_and_saveexec_b64 s[2:3], s[0:1]
	s_cbranch_execz .LBB0_2755
	s_waitcnt vmcnt(0) lgkmcnt(0)
	v_mov_b32_e32 v241, 0
	v_lshlrev_b32_e64 v254, 8, s31
	v_mov_b32_e32 v247, 1
	v_add_u32_e32 v246, 0x1400, v254
	global_atomic_add v248, v246, v247, s[60:61] sc0
	buffer_inv sc1

.LBB0_2844:
	s_cmp_lt_i32 s59, 18
	s_cbranch_scc1 .Lsb14
	s_waitcnt vmcnt(0)
	s_barrier
	s_and_saveexec_b64 s[2:3], s[0:1]
	s_cbranch_execz .LBB0_2897
	s_waitcnt vmcnt(0) lgkmcnt(0)
	v_mov_b32_e32 v241, 0
	v_lshlrev_b32_e64 v254, 8, s31
	v_mov_b32_e32 v247, 1
	v_add_u32_e32 v246, 0x1400, v254
	global_atomic_add v248, v246, v247, s[60:61] sc0
	buffer_inv sc1

.LBB0_3024:
	s_cmp_lt_i32 s59, 20
	s_waitcnt vmcnt(0)
	s_cbranch_scc1 .Lsb15
	s_waitcnt vmcnt(0)
	s_barrier
	s_and_saveexec_b64 s[2:3], s[0:1]
	s_cbranch_execz .LBB0_3077
	s_waitcnt vmcnt(0) lgkmcnt(0)
	v_mov_b32_e32 v241, 0
	v_lshlrev_b32_e64 v254, 8, s31
	v_mov_b32_e32 v247, 1
	v_add_u32_e32 v246, 0x1400, v254
	global_atomic_add v248, v246, v247, s[60:61] sc0
	buffer_inv sc1

.LBB0_3155:
	s_cmp_lt_i32 s59, 22
	s_waitcnt vmcnt(0)
	s_cbranch_scc1 .Lsb16
	s_waitcnt vmcnt(0)
	s_setprio 0
	s_barrier
	s_and_saveexec_b64 s[2:3], s[0:1]
	s_cbranch_execz .LBB0_3208
	s_waitcnt vmcnt(0) lgkmcnt(0)
	v_mov_b32_e32 v241, 0
	v_lshlrev_b32_e64 v254, 8, s31
	v_mov_b32_e32 v247, 1
	v_mov_b32_e32 v246, 0x3600
	global_atomic_add v248, v246, v247, s[60:61] sc0
	buffer_inv sc1

.LBB0_3217:
	s_cmp_lt_i32 s59, 23
	s_cbranch_scc1 .Lsb17
	s_waitcnt vmcnt(0)
	s_barrier
	s_and_saveexec_b64 s[2:3], s[0:1]
	s_cbranch_execz .LBB0_3270
	s_waitcnt vmcnt(0) lgkmcnt(0)
	v_mov_b32_e32 v241, 0
	v_lshlrev_b32_e64 v254, 8, s31
	v_mov_b32_e32 v247, 1
	v_add_u32_e32 v246, 0x1400, v254
	global_atomic_add v248, v246, v247, s[60:61] sc0
	buffer_inv sc1

.LBB0_3341:
	s_cmp_lt_i32 s59, 24
	s_waitcnt lgkmcnt(0)
	s_cbranch_scc1 .Lsb18
	s_waitcnt vmcnt(0)
	s_setprio 0
	s_barrier
	s_and_saveexec_b64 s[2:3], s[0:1]
	s_cbranch_execz .LBB0_3394
	s_waitcnt vmcnt(0) lgkmcnt(0)
	v_mov_b32_e32 v241, 0
	v_lshlrev_b32_e64 v254, 8, s31
	v_mov_b32_e32 v247, 1
	v_mov_b32_e32 v246, 0x3600
	global_atomic_add v248, v246, v247, s[60:61] sc0
	buffer_inv sc1

.LBB0_3517:
	s_cmp_lt_i32 s59, 26
	s_waitcnt vmcnt(0)
	s_cbranch_scc1 .Lsb19
	s_waitcnt vmcnt(0)
	s_setprio 0
	s_barrier
	s_and_saveexec_b64 s[2:3], s[0:1]
	s_cbranch_execz .LBB0_3570
	s_waitcnt vmcnt(0) lgkmcnt(0)
	v_mov_b32_e32 v241, 0
	v_lshlrev_b32_e64 v254, 8, s31
	v_mov_b32_e32 v247, 1
	v_mov_b32_e32 v246, 0x3600
	global_atomic_add v248, v246, v247, s[60:61] sc0
	buffer_inv sc1
